# scan inner loop re-laid out: 2 state rows x 4 columns per lane (row pair packed in one pk register), 16-lane DPP row reductions, halves LDS vector reads per step
# baseline (speedup 1.0000x reference)
.LBB0_642:
	s_or_b64 exec, exec, s[6:7]
	s_and_b32 s12, s22, 1
	s_and_b64 s[6:7], s[50:51], exec
	s_mov_b32 s1, 0x1a160000
	s_cselect_b32 s6, s1, 0x1b360000
	s_add_u32 s6, s94, s6
	s_addc_u32 s7, s95, 0
	s_lshl_b32 s13, s12, 5
	v_lshlrev_b32_e32 v158, 3, v81
	v_lshrrev_b32_e32 v79, 3, v79
	v_lshl_add_u32 v83, v87, 3, s13
	v_or_b32_e32 v179, v83, v79
	v_lshlrev_b32_e32 v79, 2, v158
	v_readlane_b32 s13, v252, 11
	v_lshl_add_u32 v83, v178, 8, 0
	v_lshlrev_b32_e32 v84, 1, v158
	v_add_u32_e32 v180, s13, v79
	v_readlane_b32 s13, v252, 12
	v_lshl_add_u32 v188, v179, 2, 0
	v_mov_b32_e32 v159, v0
	v_add_u32_e32 v182, s13, v79
	v_readlane_b32 s13, v252, 13
	v_cmp_eq_u32_e64 s[42:43], 0, v81
	v_or_b32_e32 v81, s12, v81
	v_add_u32_e32 v183, s13, v79
	v_readlane_b32 s13, v252, 14
	v_bfe_u32 v1, v80, 4, 2
	v_cmp_eq_u32_e64 s[44:45], 0, v81
	v_add_u32_e32 v184, s13, v79
	v_readlane_b32 s13, v252, 23
	v_lshlrev_b32_e32 v80, 3, v1
	v_add_u32_e32 v181, v83, v79
	v_add_u32_e32 v185, s13, v79
	s_movk_i32 s13, 0xff90
	v_mul_lo_u32 v85, v178, s13
	v_readlane_b32 s13, v253, 18
	v_add3_u32 v186, v83, v85, v84
	v_mov_b32_e32 v85, v0
	v_add_u32_e32 v187, s13, v79
	s_add_u32 s13, s6, s52
	s_addc_u32 s14, s7, 0
	s_and_b64 s[6:7], s[50:51], exec
	s_cselect_b32 s6, 0, 0x7c0
	v_lshl_add_u64 v[160:161], s[80:81], 0, v[84:85]
	v_or_b32_e32 v84, s6, v158
	v_lshl_add_u32 v190, s6, 2, v188
	s_lshl_b32 s6, s12, 7
	v_add3_u32 v191, v83, s6, v82
	s_lshl_b32 s6, s12, 6
	s_add_u32 s6, s13, s6
	s_addc_u32 s7, s14, 0
	v_lshl_add_u64 v[162:163], s[6:7], 0, v[158:159]
	s_movk_i32 s6, 0xff04
	v_mul_lo_u32 v81, v178, s6
	s_lshl_b32 s6, s11, 3
	v_readlane_b32 s12, v252, 5
	v_readlane_b32 s13, v252, 6
	s_add_u32 s6, s12, s6
	v_lshlrev_b32_e32 v79, 1, v80
	v_lshlrev_b32_e32 v80, 7, v87
	s_addc_u32 s7, s13, 0
	s_lshl_b32 s10, s10, 2
	v_mul_u32_u24_e32 v82, 0x48, v86
	v_lshl_add_u32 v78, v1, 8, v78
	v_lshlrev_b32_e32 v1, 4, v1
	s_add_u32 s54, s6, s10
	v_lshlrev_b32_e32 v82, 1, v82
	v_lshl_add_u32 v193, v78, 2, 0
	v_add3_u32 v194, 0, v80, v1
	v_mov_b32_e32 v1, v0
	s_mov_b32 s1, 0
	v_cmp_eq_u32_e64 s[40:41], 0, v86
	v_lshl_add_u32 v189, v84, 2, 0
	v_and_b32_e32 v212, 63, v234
	v_and_b32_e32 v213, 0xffffff00, v189
	v_and_b32_e32 v214, 15, v212
	v_lshl_or_b32 v189, v214, 4, v213
	v_and_b32_e32 v214, 0xffffffe0, v188
	v_lshrrev_b32_e32 v215, 4, v212
	v_and_b32_e32 v212, 1, v212
	v_lshl_add_u32 v214, v215, 3, v214
	v_lshl_add_u32 v214, v212, 2, v214
	v_add_u32_e32 v190, v213, v214
	v_xor_b32_e32 v210, 4, v190
	v_add_u32_e32 v192, s79, v178
	s_addc_u32 s55, s7, 0
	v_add3_u32 v159, 0, v79, v82
	v_add_u32_e32 v195, 0x100, v193
	v_add_u32_e32 v196, 0x200, v193
	v_add_u32_e32 v197, 0x300, v193
	v_add_u32_e32 v198, 0x1000, v193
	v_add_u32_e32 v199, 0x1100, v193
	v_add_u32_e32 v200, 0x1200, v193
	v_add_u32_e32 v201, 0x1300, v193
	v_add_u32_e32 v202, v83, v81
	v_mov_b64_e32 v[164:165], v[0:1]
	v_mov_b64_e32 v[166:167], v[0:1]
	v_mov_b64_e32 v[168:169], v[0:1]
	v_mov_b64_e32 v[170:171], v[0:1]
	s_waitcnt vmcnt(0) lgkmcnt(0)
	s_barrier
	s_branch .LBB0_644

.LBB0_682:
	s_waitcnt lgkmcnt(0)
	s_barrier
	ds_read_b128 v[78:81], v189 offset:16384
	ds_read_b128 v[82:85], v189 offset:40960
	ds_read_b128 v[86:89], v189 offset:24576
	ds_read_b128 v[90:93], v189 offset:32768
	ds_read_b128 v[94:97], v189
	ds_read_b32 v98, v190 offset:8192
	ds_read_b32 v99, v210 offset:8192
	s_and_b64 vcc, exec, s[50:51]
	s_cbranch_vccz .Lscan_rev
	s_movk_i32 s12, 0x400
	v_mov_b32_e32 v207, v189
	v_mov_b32_e32 v208, v190
	v_mov_b32_e32 v209, v190
	v_mov_b32_e32 v211, v210
	s_waitcnt lgkmcnt(0)
	ds_read_b128 v[118:121], v207 offset:16640
	ds_read_b128 v[122:125], v207 offset:41216
	ds_read_b128 v[126:129], v207 offset:24832
	ds_read_b128 v[130:133], v207 offset:33024
	ds_read_b128 v[134:137], v207 offset:256
	ds_read_b32 v138, v208 offset:8448
	ds_read_b32 v139, v211 offset:8448
	v_pk_mul_f32 v[212:213], v[164:165], v[78:79] op_sel_hi:[1,0]
	v_pk_fma_f32 v[212:213], v[166:167], v[78:79], v[212:213] op_sel:[0,1,0] op_sel_hi:[1,1,1]
	v_pk_fma_f32 v[212:213], v[168:169], v[80:81], v[212:213] op_sel_hi:[1,0,1]
	v_pk_fma_f32 v[212:213], v[170:171], v[80:81], v[212:213] op_sel:[0,1,0] op_sel_hi:[1,1,1]
	v_pk_mul_f32 v[164:165], v[90:91], v[164:165] op_sel_hi:[0,1]
	v_pk_mul_f32 v[166:167], v[90:91], v[166:167] op_sel:[1,0] op_sel_hi:[1,1]
	v_add_f32_dpp v220, v213, v212 quad_perm:[1,0,3,2] row_mask:0xf bank_mask:0xf
	v_pk_mul_f32 v[168:169], v[92:93], v[168:169] op_sel_hi:[0,1]
	v_pk_mul_f32 v[170:171], v[92:93], v[170:171] op_sel:[1,0] op_sel_hi:[1,1]
	v_add_f32_dpp v220, v220, v220 quad_perm:[2,3,0,1] row_mask:0xf bank_mask:0xf
	v_pk_fma_f32 v[164:165], v[86:87], v[98:99], v[164:165] op_sel_hi:[0,1,1]
	v_pk_fma_f32 v[166:167], v[86:87], v[98:99], v[166:167] op_sel:[1,0,0] op_sel_hi:[1,1,1]
	v_add_f32_dpp v220, v220, v220 row_ror:4 row_mask:0xf bank_mask:0xf
	v_pk_fma_f32 v[168:169], v[88:89], v[98:99], v[168:169] op_sel_hi:[0,1,1]
	v_pk_fma_f32 v[170:171], v[88:89], v[98:99], v[170:171] op_sel:[1,0,0] op_sel_hi:[1,1,1]
	v_add_f32_dpp v220, v220, v220 row_ror:8 row_mask:0xf bank_mask:0xf
	s_nop 1
	v_mov_b32_dpp v221, v220 quad_perm:[1,0,3,2] row_mask:0xf bank_mask:0xf
	v_pk_fma_f32 v[164:165], v[82:83], v[220:221], v[164:165] op_sel_hi:[0,1,1] neg_lo:[0,1,0] neg_hi:[0,1,0]
	v_pk_fma_f32 v[166:167], v[82:83], v[220:221], v[166:167] op_sel:[1,0,0] op_sel_hi:[1,1,1] neg_lo:[0,1,0] neg_hi:[0,1,0]
	v_pk_fma_f32 v[168:169], v[84:85], v[220:221], v[168:169] op_sel_hi:[0,1,1] neg_lo:[0,1,0] neg_hi:[0,1,0]
	v_pk_fma_f32 v[170:171], v[84:85], v[220:221], v[170:171] op_sel:[1,0,0] op_sel_hi:[1,1,1] neg_lo:[0,1,0] neg_hi:[0,1,0]
	v_pk_mul_f32 v[216:217], v[164:165], v[94:95] op_sel_hi:[1,0]
	v_pk_fma_f32 v[216:217], v[166:167], v[94:95], v[216:217] op_sel:[0,1,0] op_sel_hi:[1,1,1]
	v_pk_fma_f32 v[216:217], v[168:169], v[96:97], v[216:217] op_sel_hi:[1,0,1]
	v_pk_fma_f32 v[216:217], v[170:171], v[96:97], v[216:217] op_sel:[0,1,0] op_sel_hi:[1,1,1]
	s_waitcnt lgkmcnt(0)
	ds_read_b128 v[78:81], v207 offset:16896
	ds_read_b128 v[82:85], v207 offset:41472
	ds_read_b128 v[86:89], v207 offset:25088
	ds_read_b128 v[90:93], v207 offset:33280
	ds_read_b128 v[94:97], v207 offset:512
	ds_read_b32 v98, v208 offset:8704
	ds_read_b32 v99, v211 offset:8704
	v_pk_mul_f32 v[212:213], v[164:165], v[118:119] op_sel_hi:[1,0]
	v_pk_fma_f32 v[212:213], v[166:167], v[118:119], v[212:213] op_sel:[0,1,0] op_sel_hi:[1,1,1]
	v_add_f32_dpp v224, v217, v216 quad_perm:[1,0,3,2] row_mask:0xf bank_mask:0xf
	v_pk_fma_f32 v[212:213], v[168:169], v[120:121], v[212:213] op_sel_hi:[1,0,1]
	v_pk_fma_f32 v[212:213], v[170:171], v[120:121], v[212:213] op_sel:[0,1,0] op_sel_hi:[1,1,1]
	v_add_f32_dpp v224, v224, v224 quad_perm:[2,3,0,1] row_mask:0xf bank_mask:0xf
	v_pk_mul_f32 v[164:165], v[130:131], v[164:165] op_sel_hi:[0,1]
	v_pk_mul_f32 v[166:167], v[130:131], v[166:167] op_sel:[1,0] op_sel_hi:[1,1]
	v_add_f32_dpp v220, v213, v212 quad_perm:[1,0,3,2] row_mask:0xf bank_mask:0xf
	v_add_f32_dpp v224, v224, v224 row_ror:4 row_mask:0xf bank_mask:0xf
	v_pk_mul_f32 v[168:169], v[132:133], v[168:169] op_sel_hi:[0,1]
	v_add_f32_dpp v220, v220, v220 quad_perm:[2,3,0,1] row_mask:0xf bank_mask:0xf
	v_add_f32_dpp v224, v224, v224 row_ror:8 row_mask:0xf bank_mask:0xf
	v_pk_mul_f32 v[170:171], v[132:133], v[170:171] op_sel:[1,0] op_sel_hi:[1,1]
	v_pk_fma_f32 v[164:165], v[126:127], v[138:139], v[164:165] op_sel_hi:[0,1,1]
	v_add_f32_dpp v220, v220, v220 row_ror:4 row_mask:0xf bank_mask:0xf
	ds_write_b32 v209, v224 offset:49152
	v_pk_fma_f32 v[166:167], v[126:127], v[138:139], v[166:167] op_sel:[1,0,0] op_sel_hi:[1,1,1]
	v_pk_fma_f32 v[168:169], v[128:129], v[138:139], v[168:169] op_sel_hi:[0,1,1]
	v_add_f32_dpp v220, v220, v220 row_ror:8 row_mask:0xf bank_mask:0xf
	v_pk_fma_f32 v[170:171], v[128:129], v[138:139], v[170:171] op_sel:[1,0,0] op_sel_hi:[1,1,1]
	s_nop 0
	v_mov_b32_dpp v221, v220 quad_perm:[1,0,3,2] row_mask:0xf bank_mask:0xf
	v_pk_fma_f32 v[164:165], v[122:123], v[220:221], v[164:165] op_sel_hi:[0,1,1] neg_lo:[0,1,0] neg_hi:[0,1,0]
	v_pk_fma_f32 v[166:167], v[122:123], v[220:221], v[166:167] op_sel:[1,0,0] op_sel_hi:[1,1,1] neg_lo:[0,1,0] neg_hi:[0,1,0]
	v_pk_fma_f32 v[168:169], v[124:125], v[220:221], v[168:169] op_sel_hi:[0,1,1] neg_lo:[0,1,0] neg_hi:[0,1,0]
	v_pk_fma_f32 v[170:171], v[124:125], v[220:221], v[170:171] op_sel:[1,0,0] op_sel_hi:[1,1,1] neg_lo:[0,1,0] neg_hi:[0,1,0]
	v_pk_mul_f32 v[216:217], v[164:165], v[134:135] op_sel_hi:[1,0]
	v_pk_fma_f32 v[216:217], v[166:167], v[134:135], v[216:217] op_sel:[0,1,0] op_sel_hi:[1,1,1]
	v_pk_fma_f32 v[216:217], v[168:169], v[136:137], v[216:217] op_sel_hi:[1,0,1]
	v_pk_fma_f32 v[216:217], v[170:171], v[136:137], v[216:217] op_sel:[0,1,0] op_sel_hi:[1,1,1]
	s_waitcnt lgkmcnt(0)
	ds_read_b128 v[118:121], v207 offset:17152
	ds_read_b128 v[122:125], v207 offset:41728
	ds_read_b128 v[126:129], v207 offset:25344
	ds_read_b128 v[130:133], v207 offset:33536
	ds_read_b128 v[134:137], v207 offset:768
	ds_read_b32 v138, v208 offset:8960
	ds_read_b32 v139, v211 offset:8960
	v_pk_mul_f32 v[212:213], v[164:165], v[78:79] op_sel_hi:[1,0]
	v_pk_fma_f32 v[212:213], v[166:167], v[78:79], v[212:213] op_sel:[0,1,0] op_sel_hi:[1,1,1]
	v_add_f32_dpp v224, v217, v216 quad_perm:[1,0,3,2] row_mask:0xf bank_mask:0xf
	v_pk_fma_f32 v[212:213], v[168:169], v[80:81], v[212:213] op_sel_hi:[1,0,1]
	v_pk_fma_f32 v[212:213], v[170:171], v[80:81], v[212:213] op_sel:[0,1,0] op_sel_hi:[1,1,1]
	v_add_f32_dpp v224, v224, v224 quad_perm:[2,3,0,1] row_mask:0xf bank_mask:0xf
	v_pk_mul_f32 v[164:165], v[90:91], v[164:165] op_sel_hi:[0,1]
	v_pk_mul_f32 v[166:167], v[90:91], v[166:167] op_sel:[1,0] op_sel_hi:[1,1]
	v_add_f32_dpp v220, v213, v212 quad_perm:[1,0,3,2] row_mask:0xf bank_mask:0xf
	v_add_f32_dpp v224, v224, v224 row_ror:4 row_mask:0xf bank_mask:0xf
	v_pk_mul_f32 v[168:169], v[92:93], v[168:169] op_sel_hi:[0,1]
	v_add_f32_dpp v220, v220, v220 quad_perm:[2,3,0,1] row_mask:0xf bank_mask:0xf
	v_add_f32_dpp v224, v224, v224 row_ror:8 row_mask:0xf bank_mask:0xf
	v_pk_mul_f32 v[170:171], v[92:93], v[170:171] op_sel:[1,0] op_sel_hi:[1,1]
	v_pk_fma_f32 v[164:165], v[86:87], v[98:99], v[164:165] op_sel_hi:[0,1,1]
	v_add_f32_dpp v220, v220, v220 row_ror:4 row_mask:0xf bank_mask:0xf
	ds_write_b32 v209, v224 offset:49408
	v_pk_fma_f32 v[166:167], v[86:87], v[98:99], v[166:167] op_sel:[1,0,0] op_sel_hi:[1,1,1]
	v_pk_fma_f32 v[168:169], v[88:89], v[98:99], v[168:169] op_sel_hi:[0,1,1]
	v_add_f32_dpp v220, v220, v220 row_ror:8 row_mask:0xf bank_mask:0xf
	v_pk_fma_f32 v[170:171], v[88:89], v[98:99], v[170:171] op_sel:[1,0,0] op_sel_hi:[1,1,1]
	s_nop 0
	v_mov_b32_dpp v221, v220 quad_perm:[1,0,3,2] row_mask:0xf bank_mask:0xf
	v_pk_fma_f32 v[164:165], v[82:83], v[220:221], v[164:165] op_sel_hi:[0,1,1] neg_lo:[0,1,0] neg_hi:[0,1,0]
	v_pk_fma_f32 v[166:167], v[82:83], v[220:221], v[166:167] op_sel:[1,0,0] op_sel_hi:[1,1,1] neg_lo:[0,1,0] neg_hi:[0,1,0]
	v_pk_fma_f32 v[168:169], v[84:85], v[220:221], v[168:169] op_sel_hi:[0,1,1] neg_lo:[0,1,0] neg_hi:[0,1,0]
	v_pk_fma_f32 v[170:171], v[84:85], v[220:221], v[170:171] op_sel:[1,0,0] op_sel_hi:[1,1,1] neg_lo:[0,1,0] neg_hi:[0,1,0]
	v_pk_mul_f32 v[216:217], v[164:165], v[94:95] op_sel_hi:[1,0]
	v_pk_fma_f32 v[216:217], v[166:167], v[94:95], v[216:217] op_sel:[0,1,0] op_sel_hi:[1,1,1]
	v_pk_fma_f32 v[216:217], v[168:169], v[96:97], v[216:217] op_sel_hi:[1,0,1]
	v_pk_fma_f32 v[216:217], v[170:171], v[96:97], v[216:217] op_sel:[0,1,0] op_sel_hi:[1,1,1]
	s_waitcnt lgkmcnt(0)
	v_add_u32_e32 v207, s12, v207
	v_add_u32_e32 v208, s12, v208
	v_add_u32_e32 v211, s12, v211
	ds_read_b128 v[78:81], v207 offset:16384
	ds_read_b128 v[82:85], v207 offset:40960
	ds_read_b128 v[86:89], v207 offset:24576
	ds_read_b128 v[90:93], v207 offset:32768
	ds_read_b128 v[94:97], v207 offset:0
	ds_read_b32 v98, v208 offset:8192
	ds_read_b32 v99, v211 offset:8192
	v_pk_mul_f32 v[212:213], v[164:165], v[118:119] op_sel_hi:[1,0]
	v_pk_fma_f32 v[212:213], v[166:167], v[118:119], v[212:213] op_sel:[0,1,0] op_sel_hi:[1,1,1]
	v_add_f32_dpp v224, v217, v216 quad_perm:[1,0,3,2] row_mask:0xf bank_mask:0xf
	v_pk_fma_f32 v[212:213], v[168:169], v[120:121], v[212:213] op_sel_hi:[1,0,1]
	v_pk_fma_f32 v[212:213], v[170:171], v[120:121], v[212:213] op_sel:[0,1,0] op_sel_hi:[1,1,1]
	v_add_f32_dpp v224, v224, v224 quad_perm:[2,3,0,1] row_mask:0xf bank_mask:0xf
	v_pk_mul_f32 v[164:165], v[130:131], v[164:165] op_sel_hi:[0,1]
	v_pk_mul_f32 v[166:167], v[130:131], v[166:167] op_sel:[1,0] op_sel_hi:[1,1]
	v_add_f32_dpp v220, v213, v212 quad_perm:[1,0,3,2] row_mask:0xf bank_mask:0xf
	v_add_f32_dpp v224, v224, v224 row_ror:4 row_mask:0xf bank_mask:0xf
	v_pk_mul_f32 v[168:169], v[132:133], v[168:169] op_sel_hi:[0,1]
	v_add_f32_dpp v220, v220, v220 quad_perm:[2,3,0,1] row_mask:0xf bank_mask:0xf
	v_add_f32_dpp v224, v224, v224 row_ror:8 row_mask:0xf bank_mask:0xf
	v_pk_mul_f32 v[170:171], v[132:133], v[170:171] op_sel:[1,0] op_sel_hi:[1,1]
	v_pk_fma_f32 v[164:165], v[126:127], v[138:139], v[164:165] op_sel_hi:[0,1,1]
	v_add_f32_dpp v220, v220, v220 row_ror:4 row_mask:0xf bank_mask:0xf
	ds_write_b32 v209, v224 offset:49664
	v_pk_fma_f32 v[166:167], v[126:127], v[138:139], v[166:167] op_sel:[1,0,0] op_sel_hi:[1,1,1]
	v_pk_fma_f32 v[168:169], v[128:129], v[138:139], v[168:169] op_sel_hi:[0,1,1]
	v_add_f32_dpp v220, v220, v220 row_ror:8 row_mask:0xf bank_mask:0xf
	v_pk_fma_f32 v[170:171], v[128:129], v[138:139], v[170:171] op_sel:[1,0,0] op_sel_hi:[1,1,1]
	s_nop 0
	v_mov_b32_dpp v221, v220 quad_perm:[1,0,3,2] row_mask:0xf bank_mask:0xf
	v_pk_fma_f32 v[164:165], v[122:123], v[220:221], v[164:165] op_sel_hi:[0,1,1] neg_lo:[0,1,0] neg_hi:[0,1,0]
	v_pk_fma_f32 v[166:167], v[122:123], v[220:221], v[166:167] op_sel:[1,0,0] op_sel_hi:[1,1,1] neg_lo:[0,1,0] neg_hi:[0,1,0]
	v_pk_fma_f32 v[168:169], v[124:125], v[220:221], v[168:169] op_sel_hi:[0,1,1] neg_lo:[0,1,0] neg_hi:[0,1,0]
	v_pk_fma_f32 v[170:171], v[124:125], v[220:221], v[170:171] op_sel:[1,0,0] op_sel_hi:[1,1,1] neg_lo:[0,1,0] neg_hi:[0,1,0]
	v_pk_mul_f32 v[216:217], v[164:165], v[134:135] op_sel_hi:[1,0]
	v_pk_fma_f32 v[216:217], v[166:167], v[134:135], v[216:217] op_sel:[0,1,0] op_sel_hi:[1,1,1]
	v_pk_fma_f32 v[216:217], v[168:169], v[136:137], v[216:217] op_sel_hi:[1,0,1]
	v_pk_fma_f32 v[216:217], v[170:171], v[136:137], v[216:217] op_sel:[0,1,0] op_sel_hi:[1,1,1]
	s_mov_b32 s11, 1
.Lscan_fwd_loop:
	s_waitcnt lgkmcnt(0)
	ds_read_b128 v[118:121], v207 offset:16640
	ds_read_b128 v[122:125], v207 offset:41216
	ds_read_b128 v[126:129], v207 offset:24832
	ds_read_b128 v[130:133], v207 offset:33024
	ds_read_b128 v[134:137], v207 offset:256
	ds_read_b32 v138, v208 offset:8448
	ds_read_b32 v139, v211 offset:8448
	v_pk_mul_f32 v[212:213], v[164:165], v[78:79] op_sel_hi:[1,0]
	v_pk_fma_f32 v[212:213], v[166:167], v[78:79], v[212:213] op_sel:[0,1,0] op_sel_hi:[1,1,1]
	v_add_f32_dpp v224, v217, v216 quad_perm:[1,0,3,2] row_mask:0xf bank_mask:0xf
	v_pk_fma_f32 v[212:213], v[168:169], v[80:81], v[212:213] op_sel_hi:[1,0,1]
	v_pk_fma_f32 v[212:213], v[170:171], v[80:81], v[212:213] op_sel:[0,1,0] op_sel_hi:[1,1,1]
	v_add_f32_dpp v224, v224, v224 quad_perm:[2,3,0,1] row_mask:0xf bank_mask:0xf
	v_pk_mul_f32 v[164:165], v[90:91], v[164:165] op_sel_hi:[0,1]
	v_pk_mul_f32 v[166:167], v[90:91], v[166:167] op_sel:[1,0] op_sel_hi:[1,1]
	v_add_f32_dpp v220, v213, v212 quad_perm:[1,0,3,2] row_mask:0xf bank_mask:0xf
	v_add_f32_dpp v224, v224, v224 row_ror:4 row_mask:0xf bank_mask:0xf
	v_pk_mul_f32 v[168:169], v[92:93], v[168:169] op_sel_hi:[0,1]
	v_add_f32_dpp v220, v220, v220 quad_perm:[2,3,0,1] row_mask:0xf bank_mask:0xf
	v_add_f32_dpp v224, v224, v224 row_ror:8 row_mask:0xf bank_mask:0xf
	v_pk_mul_f32 v[170:171], v[92:93], v[170:171] op_sel:[1,0] op_sel_hi:[1,1]
	v_pk_fma_f32 v[164:165], v[86:87], v[98:99], v[164:165] op_sel_hi:[0,1,1]
	v_add_f32_dpp v220, v220, v220 row_ror:4 row_mask:0xf bank_mask:0xf
	ds_write_b32 v209, v224 offset:49920
	v_add_u32_e32 v209, s12, v209
	v_pk_fma_f32 v[166:167], v[86:87], v[98:99], v[166:167] op_sel:[1,0,0] op_sel_hi:[1,1,1]
	v_pk_fma_f32 v[168:169], v[88:89], v[98:99], v[168:169] op_sel_hi:[0,1,1]
	v_add_f32_dpp v220, v220, v220 row_ror:8 row_mask:0xf bank_mask:0xf
	v_pk_fma_f32 v[170:171], v[88:89], v[98:99], v[170:171] op_sel:[1,0,0] op_sel_hi:[1,1,1]
	s_nop 0
	v_mov_b32_dpp v221, v220 quad_perm:[1,0,3,2] row_mask:0xf bank_mask:0xf
	v_pk_fma_f32 v[164:165], v[82:83], v[220:221], v[164:165] op_sel_hi:[0,1,1] neg_lo:[0,1,0] neg_hi:[0,1,0]
	v_pk_fma_f32 v[166:167], v[82:83], v[220:221], v[166:167] op_sel:[1,0,0] op_sel_hi:[1,1,1] neg_lo:[0,1,0] neg_hi:[0,1,0]
	v_pk_fma_f32 v[168:169], v[84:85], v[220:221], v[168:169] op_sel_hi:[0,1,1] neg_lo:[0,1,0] neg_hi:[0,1,0]
	v_pk_fma_f32 v[170:171], v[84:85], v[220:221], v[170:171] op_sel:[1,0,0] op_sel_hi:[1,1,1] neg_lo:[0,1,0] neg_hi:[0,1,0]
	v_pk_mul_f32 v[216:217], v[164:165], v[94:95] op_sel_hi:[1,0]
	v_pk_fma_f32 v[216:217], v[166:167], v[94:95], v[216:217] op_sel:[0,1,0] op_sel_hi:[1,1,1]
	v_pk_fma_f32 v[216:217], v[168:169], v[96:97], v[216:217] op_sel_hi:[1,0,1]
	v_pk_fma_f32 v[216:217], v[170:171], v[96:97], v[216:217] op_sel:[0,1,0] op_sel_hi:[1,1,1]
	s_waitcnt lgkmcnt(0)
	ds_read_b128 v[78:81], v207 offset:16896
	ds_read_b128 v[82:85], v207 offset:41472
	ds_read_b128 v[86:89], v207 offset:25088
	ds_read_b128 v[90:93], v207 offset:33280
	ds_read_b128 v[94:97], v207 offset:512
	ds_read_b32 v98, v208 offset:8704
	ds_read_b32 v99, v211 offset:8704
	v_pk_mul_f32 v[212:213], v[164:165], v[118:119] op_sel_hi:[1,0]
	v_pk_fma_f32 v[212:213], v[166:167], v[118:119], v[212:213] op_sel:[0,1,0] op_sel_hi:[1,1,1]
	v_add_f32_dpp v224, v217, v216 quad_perm:[1,0,3,2] row_mask:0xf bank_mask:0xf
	v_pk_fma_f32 v[212:213], v[168:169], v[120:121], v[212:213] op_sel_hi:[1,0,1]
	v_pk_fma_f32 v[212:213], v[170:171], v[120:121], v[212:213] op_sel:[0,1,0] op_sel_hi:[1,1,1]
	v_add_f32_dpp v224, v224, v224 quad_perm:[2,3,0,1] row_mask:0xf bank_mask:0xf
	v_pk_mul_f32 v[164:165], v[130:131], v[164:165] op_sel_hi:[0,1]
	v_pk_mul_f32 v[166:167], v[130:131], v[166:167] op_sel:[1,0] op_sel_hi:[1,1]
	v_add_f32_dpp v220, v213, v212 quad_perm:[1,0,3,2] row_mask:0xf bank_mask:0xf
	v_add_f32_dpp v224, v224, v224 row_ror:4 row_mask:0xf bank_mask:0xf
	v_pk_mul_f32 v[168:169], v[132:133], v[168:169] op_sel_hi:[0,1]
	v_add_f32_dpp v220, v220, v220 quad_perm:[2,3,0,1] row_mask:0xf bank_mask:0xf
	v_add_f32_dpp v224, v224, v224 row_ror:8 row_mask:0xf bank_mask:0xf
	v_pk_mul_f32 v[170:171], v[132:133], v[170:171] op_sel:[1,0] op_sel_hi:[1,1]
	v_pk_fma_f32 v[164:165], v[126:127], v[138:139], v[164:165] op_sel_hi:[0,1,1]
	v_add_f32_dpp v220, v220, v220 row_ror:4 row_mask:0xf bank_mask:0xf
	ds_write_b32 v209, v224 offset:49152
	v_pk_fma_f32 v[166:167], v[126:127], v[138:139], v[166:167] op_sel:[1,0,0] op_sel_hi:[1,1,1]
	v_pk_fma_f32 v[168:169], v[128:129], v[138:139], v[168:169] op_sel_hi:[0,1,1]
	v_add_f32_dpp v220, v220, v220 row_ror:8 row_mask:0xf bank_mask:0xf
	v_pk_fma_f32 v[170:171], v[128:129], v[138:139], v[170:171] op_sel:[1,0,0] op_sel_hi:[1,1,1]
	s_nop 0
	v_mov_b32_dpp v221, v220 quad_perm:[1,0,3,2] row_mask:0xf bank_mask:0xf
	v_pk_fma_f32 v[164:165], v[122:123], v[220:221], v[164:165] op_sel_hi:[0,1,1] neg_lo:[0,1,0] neg_hi:[0,1,0]
	v_pk_fma_f32 v[166:167], v[122:123], v[220:221], v[166:167] op_sel:[1,0,0] op_sel_hi:[1,1,1] neg_lo:[0,1,0] neg_hi:[0,1,0]
	v_pk_fma_f32 v[168:169], v[124:125], v[220:221], v[168:169] op_sel_hi:[0,1,1] neg_lo:[0,1,0] neg_hi:[0,1,0]
	v_pk_fma_f32 v[170:171], v[124:125], v[220:221], v[170:171] op_sel:[1,0,0] op_sel_hi:[1,1,1] neg_lo:[0,1,0] neg_hi:[0,1,0]
	v_pk_mul_f32 v[216:217], v[164:165], v[134:135] op_sel_hi:[1,0]
	v_pk_fma_f32 v[216:217], v[166:167], v[134:135], v[216:217] op_sel:[0,1,0] op_sel_hi:[1,1,1]
	v_pk_fma_f32 v[216:217], v[168:169], v[136:137], v[216:217] op_sel_hi:[1,0,1]
	v_pk_fma_f32 v[216:217], v[170:171], v[136:137], v[216:217] op_sel:[0,1,0] op_sel_hi:[1,1,1]
	s_waitcnt lgkmcnt(0)
	ds_read_b128 v[118:121], v207 offset:17152
	ds_read_b128 v[122:125], v207 offset:41728
	ds_read_b128 v[126:129], v207 offset:25344
	ds_read_b128 v[130:133], v207 offset:33536
	ds_read_b128 v[134:137], v207 offset:768
	ds_read_b32 v138, v208 offset:8960
	ds_read_b32 v139, v211 offset:8960
	v_pk_mul_f32 v[212:213], v[164:165], v[78:79] op_sel_hi:[1,0]
	v_pk_fma_f32 v[212:213], v[166:167], v[78:79], v[212:213] op_sel:[0,1,0] op_sel_hi:[1,1,1]
	v_add_f32_dpp v224, v217, v216 quad_perm:[1,0,3,2] row_mask:0xf bank_mask:0xf
	v_pk_fma_f32 v[212:213], v[168:169], v[80:81], v[212:213] op_sel_hi:[1,0,1]
	v_pk_fma_f32 v[212:213], v[170:171], v[80:81], v[212:213] op_sel:[0,1,0] op_sel_hi:[1,1,1]
	v_add_f32_dpp v224, v224, v224 quad_perm:[2,3,0,1] row_mask:0xf bank_mask:0xf
	v_pk_mul_f32 v[164:165], v[90:91], v[164:165] op_sel_hi:[0,1]
	v_pk_mul_f32 v[166:167], v[90:91], v[166:167] op_sel:[1,0] op_sel_hi:[1,1]
	v_add_f32_dpp v220, v213, v212 quad_perm:[1,0,3,2] row_mask:0xf bank_mask:0xf
	v_add_f32_dpp v224, v224, v224 row_ror:4 row_mask:0xf bank_mask:0xf
	v_pk_mul_f32 v[168:169], v[92:93], v[168:169] op_sel_hi:[0,1]
	v_add_f32_dpp v220, v220, v220 quad_perm:[2,3,0,1] row_mask:0xf bank_mask:0xf
	v_add_f32_dpp v224, v224, v224 row_ror:8 row_mask:0xf bank_mask:0xf
	v_pk_mul_f32 v[170:171], v[92:93], v[170:171] op_sel:[1,0] op_sel_hi:[1,1]
	v_pk_fma_f32 v[164:165], v[86:87], v[98:99], v[164:165] op_sel_hi:[0,1,1]
	v_add_f32_dpp v220, v220, v220 row_ror:4 row_mask:0xf bank_mask:0xf
	ds_write_b32 v209, v224 offset:49408
	v_pk_fma_f32 v[166:167], v[86:87], v[98:99], v[166:167] op_sel:[1,0,0] op_sel_hi:[1,1,1]
	v_pk_fma_f32 v[168:169], v[88:89], v[98:99], v[168:169] op_sel_hi:[0,1,1]
	v_add_f32_dpp v220, v220, v220 row_ror:8 row_mask:0xf bank_mask:0xf
	v_pk_fma_f32 v[170:171], v[88:89], v[98:99], v[170:171] op_sel:[1,0,0] op_sel_hi:[1,1,1]
	s_nop 0
	v_mov_b32_dpp v221, v220 quad_perm:[1,0,3,2] row_mask:0xf bank_mask:0xf
	v_pk_fma_f32 v[164:165], v[82:83], v[220:221], v[164:165] op_sel_hi:[0,1,1] neg_lo:[0,1,0] neg_hi:[0,1,0]
	v_pk_fma_f32 v[166:167], v[82:83], v[220:221], v[166:167] op_sel:[1,0,0] op_sel_hi:[1,1,1] neg_lo:[0,1,0] neg_hi:[0,1,0]
	v_pk_fma_f32 v[168:169], v[84:85], v[220:221], v[168:169] op_sel_hi:[0,1,1] neg_lo:[0,1,0] neg_hi:[0,1,0]
	v_pk_fma_f32 v[170:171], v[84:85], v[220:221], v[170:171] op_sel:[1,0,0] op_sel_hi:[1,1,1] neg_lo:[0,1,0] neg_hi:[0,1,0]
	v_pk_mul_f32 v[216:217], v[164:165], v[94:95] op_sel_hi:[1,0]
	v_pk_fma_f32 v[216:217], v[166:167], v[94:95], v[216:217] op_sel:[0,1,0] op_sel_hi:[1,1,1]
	v_pk_fma_f32 v[216:217], v[168:169], v[96:97], v[216:217] op_sel_hi:[1,0,1]
	v_pk_fma_f32 v[216:217], v[170:171], v[96:97], v[216:217] op_sel:[0,1,0] op_sel_hi:[1,1,1]
	s_waitcnt lgkmcnt(0)
	s_cmp_eq_u32 s11, 7
	s_cbranch_scc1 .Lscan_fwd_nopf
	v_add_u32_e32 v207, s12, v207
	v_add_u32_e32 v208, s12, v208
	v_add_u32_e32 v211, s12, v211
	ds_read_b128 v[78:81], v207 offset:16384
	ds_read_b128 v[82:85], v207 offset:40960
	ds_read_b128 v[86:89], v207 offset:24576
	ds_read_b128 v[90:93], v207 offset:32768
	ds_read_b128 v[94:97], v207 offset:0
	ds_read_b32 v98, v208 offset:8192
	ds_read_b32 v99, v211 offset:8192
.Lscan_fwd_nopf:
	v_pk_mul_f32 v[212:213], v[164:165], v[118:119] op_sel_hi:[1,0]
	v_pk_fma_f32 v[212:213], v[166:167], v[118:119], v[212:213] op_sel:[0,1,0] op_sel_hi:[1,1,1]
	v_add_f32_dpp v224, v217, v216 quad_perm:[1,0,3,2] row_mask:0xf bank_mask:0xf
	v_pk_fma_f32 v[212:213], v[168:169], v[120:121], v[212:213] op_sel_hi:[1,0,1]
	v_pk_fma_f32 v[212:213], v[170:171], v[120:121], v[212:213] op_sel:[0,1,0] op_sel_hi:[1,1,1]
	v_add_f32_dpp v224, v224, v224 quad_perm:[2,3,0,1] row_mask:0xf bank_mask:0xf
	v_pk_mul_f32 v[164:165], v[130:131], v[164:165] op_sel_hi:[0,1]
	v_pk_mul_f32 v[166:167], v[130:131], v[166:167] op_sel:[1,0] op_sel_hi:[1,1]
	v_add_f32_dpp v220, v213, v212 quad_perm:[1,0,3,2] row_mask:0xf bank_mask:0xf
	v_add_f32_dpp v224, v224, v224 row_ror:4 row_mask:0xf bank_mask:0xf
	v_pk_mul_f32 v[168:169], v[132:133], v[168:169] op_sel_hi:[0,1]
	v_add_f32_dpp v220, v220, v220 quad_perm:[2,3,0,1] row_mask:0xf bank_mask:0xf
	v_add_f32_dpp v224, v224, v224 row_ror:8 row_mask:0xf bank_mask:0xf
	v_pk_mul_f32 v[170:171], v[132:133], v[170:171] op_sel:[1,0] op_sel_hi:[1,1]
	v_pk_fma_f32 v[164:165], v[126:127], v[138:139], v[164:165] op_sel_hi:[0,1,1]
	v_add_f32_dpp v220, v220, v220 row_ror:4 row_mask:0xf bank_mask:0xf
	ds_write_b32 v209, v224 offset:49664
	v_pk_fma_f32 v[166:167], v[126:127], v[138:139], v[166:167] op_sel:[1,0,0] op_sel_hi:[1,1,1]
	v_pk_fma_f32 v[168:169], v[128:129], v[138:139], v[168:169] op_sel_hi:[0,1,1]
	v_add_f32_dpp v220, v220, v220 row_ror:8 row_mask:0xf bank_mask:0xf
	v_pk_fma_f32 v[170:171], v[128:129], v[138:139], v[170:171] op_sel:[1,0,0] op_sel_hi:[1,1,1]
	s_nop 0
	v_mov_b32_dpp v221, v220 quad_perm:[1,0,3,2] row_mask:0xf bank_mask:0xf
	v_pk_fma_f32 v[164:165], v[122:123], v[220:221], v[164:165] op_sel_hi:[0,1,1] neg_lo:[0,1,0] neg_hi:[0,1,0]
	v_pk_fma_f32 v[166:167], v[122:123], v[220:221], v[166:167] op_sel:[1,0,0] op_sel_hi:[1,1,1] neg_lo:[0,1,0] neg_hi:[0,1,0]
	v_pk_fma_f32 v[168:169], v[124:125], v[220:221], v[168:169] op_sel_hi:[0,1,1] neg_lo:[0,1,0] neg_hi:[0,1,0]
	v_pk_fma_f32 v[170:171], v[124:125], v[220:221], v[170:171] op_sel:[1,0,0] op_sel_hi:[1,1,1] neg_lo:[0,1,0] neg_hi:[0,1,0]
	v_pk_mul_f32 v[216:217], v[164:165], v[134:135] op_sel_hi:[1,0]
	v_pk_fma_f32 v[216:217], v[166:167], v[134:135], v[216:217] op_sel:[0,1,0] op_sel_hi:[1,1,1]
	v_pk_fma_f32 v[216:217], v[168:169], v[136:137], v[216:217] op_sel_hi:[1,0,1]
	v_pk_fma_f32 v[216:217], v[170:171], v[136:137], v[216:217] op_sel:[0,1,0] op_sel_hi:[1,1,1]
	s_add_i32 s11, s11, 1
	s_cmp_lg_u32 s11, 8
	s_cbranch_scc1 .Lscan_fwd_loop
	s_nop 1
	v_add_f32_dpp v224, v217, v216 quad_perm:[1,0,3,2] row_mask:0xf bank_mask:0xf
	s_nop 1
	v_add_f32_dpp v224, v224, v224 quad_perm:[2,3,0,1] row_mask:0xf bank_mask:0xf
	s_nop 1
	v_add_f32_dpp v224, v224, v224 row_ror:4 row_mask:0xf bank_mask:0xf
	s_nop 1
	v_add_f32_dpp v224, v224, v224 row_ror:8 row_mask:0xf bank_mask:0xf
	ds_write_b32 v209, v224 offset:49920
	s_branch .LBB0_691
.Lscan_rev:
	s_mov_b32 s12, 0xfffffc00
	v_add_u32_e32 v207, 0xfffffd00, v189
	v_add_u32_e32 v208, 0xfffffd00, v190
	v_add_u32_e32 v209, 0xfffffd00, v190
	v_add_u32_e32 v211, 0xfffffd00, v210
	s_waitcnt lgkmcnt(0)
	ds_read_b128 v[118:121], v207 offset:16896
	ds_read_b128 v[122:125], v207 offset:41472
	ds_read_b128 v[126:129], v207 offset:25088
	ds_read_b128 v[130:133], v207 offset:33280
	ds_read_b128 v[134:137], v207 offset:512
	ds_read_b32 v138, v208 offset:8704
	ds_read_b32 v139, v211 offset:8704
	v_pk_mul_f32 v[212:213], v[164:165], v[78:79] op_sel_hi:[1,0]
	v_pk_fma_f32 v[212:213], v[166:167], v[78:79], v[212:213] op_sel:[0,1,0] op_sel_hi:[1,1,1]
	v_pk_fma_f32 v[212:213], v[168:169], v[80:81], v[212:213] op_sel_hi:[1,0,1]
	v_pk_fma_f32 v[212:213], v[170:171], v[80:81], v[212:213] op_sel:[0,1,0] op_sel_hi:[1,1,1]
	v_pk_mul_f32 v[164:165], v[90:91], v[164:165] op_sel_hi:[0,1]
	v_pk_mul_f32 v[166:167], v[90:91], v[166:167] op_sel:[1,0] op_sel_hi:[1,1]
	v_add_f32_dpp v220, v213, v212 quad_perm:[1,0,3,2] row_mask:0xf bank_mask:0xf
	v_pk_mul_f32 v[168:169], v[92:93], v[168:169] op_sel_hi:[0,1]
	v_pk_mul_f32 v[170:171], v[92:93], v[170:171] op_sel:[1,0] op_sel_hi:[1,1]
	v_add_f32_dpp v220, v220, v220 quad_perm:[2,3,0,1] row_mask:0xf bank_mask:0xf
	v_pk_fma_f32 v[164:165], v[86:87], v[98:99], v[164:165] op_sel_hi:[0,1,1]
	v_pk_fma_f32 v[166:167], v[86:87], v[98:99], v[166:167] op_sel:[1,0,0] op_sel_hi:[1,1,1]
	v_add_f32_dpp v220, v220, v220 row_ror:4 row_mask:0xf bank_mask:0xf
	v_pk_fma_f32 v[168:169], v[88:89], v[98:99], v[168:169] op_sel_hi:[0,1,1]
	v_pk_fma_f32 v[170:171], v[88:89], v[98:99], v[170:171] op_sel:[1,0,0] op_sel_hi:[1,1,1]
	v_add_f32_dpp v220, v220, v220 row_ror:8 row_mask:0xf bank_mask:0xf
	s_nop 1
	v_mov_b32_dpp v221, v220 quad_perm:[1,0,3,2] row_mask:0xf bank_mask:0xf
	v_pk_fma_f32 v[164:165], v[82:83], v[220:221], v[164:165] op_sel_hi:[0,1,1] neg_lo:[0,1,0] neg_hi:[0,1,0]
	v_pk_fma_f32 v[166:167], v[82:83], v[220:221], v[166:167] op_sel:[1,0,0] op_sel_hi:[1,1,1] neg_lo:[0,1,0] neg_hi:[0,1,0]
	v_pk_fma_f32 v[168:169], v[84:85], v[220:221], v[168:169] op_sel_hi:[0,1,1] neg_lo:[0,1,0] neg_hi:[0,1,0]
	v_pk_fma_f32 v[170:171], v[84:85], v[220:221], v[170:171] op_sel:[1,0,0] op_sel_hi:[1,1,1] neg_lo:[0,1,0] neg_hi:[0,1,0]
	v_pk_mul_f32 v[216:217], v[164:165], v[94:95] op_sel_hi:[1,0]
	v_pk_fma_f32 v[216:217], v[166:167], v[94:95], v[216:217] op_sel:[0,1,0] op_sel_hi:[1,1,1]
	v_pk_fma_f32 v[216:217], v[168:169], v[96:97], v[216:217] op_sel_hi:[1,0,1]
	v_pk_fma_f32 v[216:217], v[170:171], v[96:97], v[216:217] op_sel:[0,1,0] op_sel_hi:[1,1,1]
	s_waitcnt lgkmcnt(0)
	ds_read_b128 v[78:81], v207 offset:16640
	ds_read_b128 v[82:85], v207 offset:41216
	ds_read_b128 v[86:89], v207 offset:24832
	ds_read_b128 v[90:93], v207 offset:33024
	ds_read_b128 v[94:97], v207 offset:256
	ds_read_b32 v98, v208 offset:8448
	ds_read_b32 v99, v211 offset:8448
	v_pk_mul_f32 v[212:213], v[164:165], v[118:119] op_sel_hi:[1,0]
	v_pk_fma_f32 v[212:213], v[166:167], v[118:119], v[212:213] op_sel:[0,1,0] op_sel_hi:[1,1,1]
	v_add_f32_dpp v224, v217, v216 quad_perm:[1,0,3,2] row_mask:0xf bank_mask:0xf
	v_pk_fma_f32 v[212:213], v[168:169], v[120:121], v[212:213] op_sel_hi:[1,0,1]
	v_pk_fma_f32 v[212:213], v[170:171], v[120:121], v[212:213] op_sel:[0,1,0] op_sel_hi:[1,1,1]
	v_add_f32_dpp v224, v224, v224 quad_perm:[2,3,0,1] row_mask:0xf bank_mask:0xf
	v_pk_mul_f32 v[164:165], v[130:131], v[164:165] op_sel_hi:[0,1]
	v_pk_mul_f32 v[166:167], v[130:131], v[166:167] op_sel:[1,0] op_sel_hi:[1,1]
	v_add_f32_dpp v220, v213, v212 quad_perm:[1,0,3,2] row_mask:0xf bank_mask:0xf
	v_add_f32_dpp v224, v224, v224 row_ror:4 row_mask:0xf bank_mask:0xf
	v_pk_mul_f32 v[168:169], v[132:133], v[168:169] op_sel_hi:[0,1]
	v_add_f32_dpp v220, v220, v220 quad_perm:[2,3,0,1] row_mask:0xf bank_mask:0xf
	v_add_f32_dpp v224, v224, v224 row_ror:8 row_mask:0xf bank_mask:0xf
	v_pk_mul_f32 v[170:171], v[132:133], v[170:171] op_sel:[1,0] op_sel_hi:[1,1]
	v_pk_fma_f32 v[164:165], v[126:127], v[138:139], v[164:165] op_sel_hi:[0,1,1]
	v_add_f32_dpp v220, v220, v220 row_ror:4 row_mask:0xf bank_mask:0xf
	ds_write_b32 v209, v224 offset:49920
	v_pk_fma_f32 v[166:167], v[126:127], v[138:139], v[166:167] op_sel:[1,0,0] op_sel_hi:[1,1,1]
	v_pk_fma_f32 v[168:169], v[128:129], v[138:139], v[168:169] op_sel_hi:[0,1,1]
	v_add_f32_dpp v220, v220, v220 row_ror:8 row_mask:0xf bank_mask:0xf
	v_pk_fma_f32 v[170:171], v[128:129], v[138:139], v[170:171] op_sel:[1,0,0] op_sel_hi:[1,1,1]
	s_nop 0
	v_mov_b32_dpp v221, v220 quad_perm:[1,0,3,2] row_mask:0xf bank_mask:0xf
	v_pk_fma_f32 v[164:165], v[122:123], v[220:221], v[164:165] op_sel_hi:[0,1,1] neg_lo:[0,1,0] neg_hi:[0,1,0]
	v_pk_fma_f32 v[166:167], v[122:123], v[220:221], v[166:167] op_sel:[1,0,0] op_sel_hi:[1,1,1] neg_lo:[0,1,0] neg_hi:[0,1,0]
	v_pk_fma_f32 v[168:169], v[124:125], v[220:221], v[168:169] op_sel_hi:[0,1,1] neg_lo:[0,1,0] neg_hi:[0,1,0]
	v_pk_fma_f32 v[170:171], v[124:125], v[220:221], v[170:171] op_sel:[1,0,0] op_sel_hi:[1,1,1] neg_lo:[0,1,0] neg_hi:[0,1,0]
	v_pk_mul_f32 v[216:217], v[164:165], v[134:135] op_sel_hi:[1,0]
	v_pk_fma_f32 v[216:217], v[166:167], v[134:135], v[216:217] op_sel:[0,1,0] op_sel_hi:[1,1,1]
	v_pk_fma_f32 v[216:217], v[168:169], v[136:137], v[216:217] op_sel_hi:[1,0,1]
	v_pk_fma_f32 v[216:217], v[170:171], v[136:137], v[216:217] op_sel:[0,1,0] op_sel_hi:[1,1,1]
	s_waitcnt lgkmcnt(0)
	ds_read_b128 v[118:121], v207 offset:16384
	ds_read_b128 v[122:125], v207 offset:40960
	ds_read_b128 v[126:129], v207 offset:24576
	ds_read_b128 v[130:133], v207 offset:32768
	ds_read_b128 v[134:137], v207 offset:0
	ds_read_b32 v138, v208 offset:8192
	ds_read_b32 v139, v211 offset:8192
	v_pk_mul_f32 v[212:213], v[164:165], v[78:79] op_sel_hi:[1,0]
	v_pk_fma_f32 v[212:213], v[166:167], v[78:79], v[212:213] op_sel:[0,1,0] op_sel_hi:[1,1,1]
	v_add_f32_dpp v224, v217, v216 quad_perm:[1,0,3,2] row_mask:0xf bank_mask:0xf
	v_pk_fma_f32 v[212:213], v[168:169], v[80:81], v[212:213] op_sel_hi:[1,0,1]
	v_pk_fma_f32 v[212:213], v[170:171], v[80:81], v[212:213] op_sel:[0,1,0] op_sel_hi:[1,1,1]
	v_add_f32_dpp v224, v224, v224 quad_perm:[2,3,0,1] row_mask:0xf bank_mask:0xf
	v_pk_mul_f32 v[164:165], v[90:91], v[164:165] op_sel_hi:[0,1]
	v_pk_mul_f32 v[166:167], v[90:91], v[166:167] op_sel:[1,0] op_sel_hi:[1,1]
	v_add_f32_dpp v220, v213, v212 quad_perm:[1,0,3,2] row_mask:0xf bank_mask:0xf
	v_add_f32_dpp v224, v224, v224 row_ror:4 row_mask:0xf bank_mask:0xf
	v_pk_mul_f32 v[168:169], v[92:93], v[168:169] op_sel_hi:[0,1]
	v_add_f32_dpp v220, v220, v220 quad_perm:[2,3,0,1] row_mask:0xf bank_mask:0xf
	v_add_f32_dpp v224, v224, v224 row_ror:8 row_mask:0xf bank_mask:0xf
	v_pk_mul_f32 v[170:171], v[92:93], v[170:171] op_sel:[1,0] op_sel_hi:[1,1]
	v_pk_fma_f32 v[164:165], v[86:87], v[98:99], v[164:165] op_sel_hi:[0,1,1]
	v_add_f32_dpp v220, v220, v220 row_ror:4 row_mask:0xf bank_mask:0xf
	ds_write_b32 v209, v224 offset:49664
	v_pk_fma_f32 v[166:167], v[86:87], v[98:99], v[166:167] op_sel:[1,0,0] op_sel_hi:[1,1,1]
	v_pk_fma_f32 v[168:169], v[88:89], v[98:99], v[168:169] op_sel_hi:[0,1,1]
	v_add_f32_dpp v220, v220, v220 row_ror:8 row_mask:0xf bank_mask:0xf
	v_pk_fma_f32 v[170:171], v[88:89], v[98:99], v[170:171] op_sel:[1,0,0] op_sel_hi:[1,1,1]
	s_nop 0
	v_mov_b32_dpp v221, v220 quad_perm:[1,0,3,2] row_mask:0xf bank_mask:0xf
	v_pk_fma_f32 v[164:165], v[82:83], v[220:221], v[164:165] op_sel_hi:[0,1,1] neg_lo:[0,1,0] neg_hi:[0,1,0]
	v_pk_fma_f32 v[166:167], v[82:83], v[220:221], v[166:167] op_sel:[1,0,0] op_sel_hi:[1,1,1] neg_lo:[0,1,0] neg_hi:[0,1,0]
	v_pk_fma_f32 v[168:169], v[84:85], v[220:221], v[168:169] op_sel_hi:[0,1,1] neg_lo:[0,1,0] neg_hi:[0,1,0]
	v_pk_fma_f32 v[170:171], v[84:85], v[220:221], v[170:171] op_sel:[1,0,0] op_sel_hi:[1,1,1] neg_lo:[0,1,0] neg_hi:[0,1,0]
	v_pk_mul_f32 v[216:217], v[164:165], v[94:95] op_sel_hi:[1,0]
	v_pk_fma_f32 v[216:217], v[166:167], v[94:95], v[216:217] op_sel:[0,1,0] op_sel_hi:[1,1,1]
	v_pk_fma_f32 v[216:217], v[168:169], v[96:97], v[216:217] op_sel_hi:[1,0,1]
	v_pk_fma_f32 v[216:217], v[170:171], v[96:97], v[216:217] op_sel:[0,1,0] op_sel_hi:[1,1,1]
	s_waitcnt lgkmcnt(0)
	v_add_u32_e32 v207, s12, v207
	v_add_u32_e32 v208, s12, v208
	v_add_u32_e32 v211, s12, v211
	ds_read_b128 v[78:81], v207 offset:17152
	ds_read_b128 v[82:85], v207 offset:41728
	ds_read_b128 v[86:89], v207 offset:25344
	ds_read_b128 v[90:93], v207 offset:33536
	ds_read_b128 v[94:97], v207 offset:768
	ds_read_b32 v98, v208 offset:8960
	ds_read_b32 v99, v211 offset:8960
	v_pk_mul_f32 v[212:213], v[164:165], v[118:119] op_sel_hi:[1,0]
	v_pk_fma_f32 v[212:213], v[166:167], v[118:119], v[212:213] op_sel:[0,1,0] op_sel_hi:[1,1,1]
	v_add_f32_dpp v224, v217, v216 quad_perm:[1,0,3,2] row_mask:0xf bank_mask:0xf
	v_pk_fma_f32 v[212:213], v[168:169], v[120:121], v[212:213] op_sel_hi:[1,0,1]
	v_pk_fma_f32 v[212:213], v[170:171], v[120:121], v[212:213] op_sel:[0,1,0] op_sel_hi:[1,1,1]
	v_add_f32_dpp v224, v224, v224 quad_perm:[2,3,0,1] row_mask:0xf bank_mask:0xf
	v_pk_mul_f32 v[164:165], v[130:131], v[164:165] op_sel_hi:[0,1]
	v_pk_mul_f32 v[166:167], v[130:131], v[166:167] op_sel:[1,0] op_sel_hi:[1,1]
	v_add_f32_dpp v220, v213, v212 quad_perm:[1,0,3,2] row_mask:0xf bank_mask:0xf
	v_add_f32_dpp v224, v224, v224 row_ror:4 row_mask:0xf bank_mask:0xf
	v_pk_mul_f32 v[168:169], v[132:133], v[168:169] op_sel_hi:[0,1]
	v_add_f32_dpp v220, v220, v220 quad_perm:[2,3,0,1] row_mask:0xf bank_mask:0xf
	v_add_f32_dpp v224, v224, v224 row_ror:8 row_mask:0xf bank_mask:0xf
	v_pk_mul_f32 v[170:171], v[132:133], v[170:171] op_sel:[1,0] op_sel_hi:[1,1]
	v_pk_fma_f32 v[164:165], v[126:127], v[138:139], v[164:165] op_sel_hi:[0,1,1]
	v_add_f32_dpp v220, v220, v220 row_ror:4 row_mask:0xf bank_mask:0xf
	ds_write_b32 v209, v224 offset:49408
	v_pk_fma_f32 v[166:167], v[126:127], v[138:139], v[166:167] op_sel:[1,0,0] op_sel_hi:[1,1,1]
	v_pk_fma_f32 v[168:169], v[128:129], v[138:139], v[168:169] op_sel_hi:[0,1,1]
	v_add_f32_dpp v220, v220, v220 row_ror:8 row_mask:0xf bank_mask:0xf
	v_pk_fma_f32 v[170:171], v[128:129], v[138:139], v[170:171] op_sel:[1,0,0] op_sel_hi:[1,1,1]
	s_nop 0
	v_mov_b32_dpp v221, v220 quad_perm:[1,0,3,2] row_mask:0xf bank_mask:0xf
	v_pk_fma_f32 v[164:165], v[122:123], v[220:221], v[164:165] op_sel_hi:[0,1,1] neg_lo:[0,1,0] neg_hi:[0,1,0]
	v_pk_fma_f32 v[166:167], v[122:123], v[220:221], v[166:167] op_sel:[1,0,0] op_sel_hi:[1,1,1] neg_lo:[0,1,0] neg_hi:[0,1,0]
	v_pk_fma_f32 v[168:169], v[124:125], v[220:221], v[168:169] op_sel_hi:[0,1,1] neg_lo:[0,1,0] neg_hi:[0,1,0]
	v_pk_fma_f32 v[170:171], v[124:125], v[220:221], v[170:171] op_sel:[1,0,0] op_sel_hi:[1,1,1] neg_lo:[0,1,0] neg_hi:[0,1,0]
	v_pk_mul_f32 v[216:217], v[164:165], v[134:135] op_sel_hi:[1,0]
	v_pk_fma_f32 v[216:217], v[166:167], v[134:135], v[216:217] op_sel:[0,1,0] op_sel_hi:[1,1,1]
	v_pk_fma_f32 v[216:217], v[168:169], v[136:137], v[216:217] op_sel_hi:[1,0,1]
	v_pk_fma_f32 v[216:217], v[170:171], v[136:137], v[216:217] op_sel:[0,1,0] op_sel_hi:[1,1,1]
	s_mov_b32 s11, 1
.Lscan_rev_loop:
	s_waitcnt lgkmcnt(0)
	ds_read_b128 v[118:121], v207 offset:16896
	ds_read_b128 v[122:125], v207 offset:41472
	ds_read_b128 v[126:129], v207 offset:25088
	ds_read_b128 v[130:133], v207 offset:33280
	ds_read_b128 v[134:137], v207 offset:512
	ds_read_b32 v138, v208 offset:8704
	ds_read_b32 v139, v211 offset:8704
	v_pk_mul_f32 v[212:213], v[164:165], v[78:79] op_sel_hi:[1,0]
	v_pk_fma_f32 v[212:213], v[166:167], v[78:79], v[212:213] op_sel:[0,1,0] op_sel_hi:[1,1,1]
	v_add_f32_dpp v224, v217, v216 quad_perm:[1,0,3,2] row_mask:0xf bank_mask:0xf
	v_pk_fma_f32 v[212:213], v[168:169], v[80:81], v[212:213] op_sel_hi:[1,0,1]
	v_pk_fma_f32 v[212:213], v[170:171], v[80:81], v[212:213] op_sel:[0,1,0] op_sel_hi:[1,1,1]
	v_add_f32_dpp v224, v224, v224 quad_perm:[2,3,0,1] row_mask:0xf bank_mask:0xf
	v_pk_mul_f32 v[164:165], v[90:91], v[164:165] op_sel_hi:[0,1]
	v_pk_mul_f32 v[166:167], v[90:91], v[166:167] op_sel:[1,0] op_sel_hi:[1,1]
	v_add_f32_dpp v220, v213, v212 quad_perm:[1,0,3,2] row_mask:0xf bank_mask:0xf
	v_add_f32_dpp v224, v224, v224 row_ror:4 row_mask:0xf bank_mask:0xf
	v_pk_mul_f32 v[168:169], v[92:93], v[168:169] op_sel_hi:[0,1]
	v_add_f32_dpp v220, v220, v220 quad_perm:[2,3,0,1] row_mask:0xf bank_mask:0xf
	v_add_f32_dpp v224, v224, v224 row_ror:8 row_mask:0xf bank_mask:0xf
	v_pk_mul_f32 v[170:171], v[92:93], v[170:171] op_sel:[1,0] op_sel_hi:[1,1]
	v_pk_fma_f32 v[164:165], v[86:87], v[98:99], v[164:165] op_sel_hi:[0,1,1]
	v_add_f32_dpp v220, v220, v220 row_ror:4 row_mask:0xf bank_mask:0xf
	ds_write_b32 v209, v224 offset:49152
	v_add_u32_e32 v209, s12, v209
	v_pk_fma_f32 v[166:167], v[86:87], v[98:99], v[166:167] op_sel:[1,0,0] op_sel_hi:[1,1,1]
	v_pk_fma_f32 v[168:169], v[88:89], v[98:99], v[168:169] op_sel_hi:[0,1,1]
	v_add_f32_dpp v220, v220, v220 row_ror:8 row_mask:0xf bank_mask:0xf
	v_pk_fma_f32 v[170:171], v[88:89], v[98:99], v[170:171] op_sel:[1,0,0] op_sel_hi:[1,1,1]
	s_nop 0
	v_mov_b32_dpp v221, v220 quad_perm:[1,0,3,2] row_mask:0xf bank_mask:0xf
	v_pk_fma_f32 v[164:165], v[82:83], v[220:221], v[164:165] op_sel_hi:[0,1,1] neg_lo:[0,1,0] neg_hi:[0,1,0]
	v_pk_fma_f32 v[166:167], v[82:83], v[220:221], v[166:167] op_sel:[1,0,0] op_sel_hi:[1,1,1] neg_lo:[0,1,0] neg_hi:[0,1,0]
	v_pk_fma_f32 v[168:169], v[84:85], v[220:221], v[168:169] op_sel_hi:[0,1,1] neg_lo:[0,1,0] neg_hi:[0,1,0]
	v_pk_fma_f32 v[170:171], v[84:85], v[220:221], v[170:171] op_sel:[1,0,0] op_sel_hi:[1,1,1] neg_lo:[0,1,0] neg_hi:[0,1,0]
	v_pk_mul_f32 v[216:217], v[164:165], v[94:95] op_sel_hi:[1,0]
	v_pk_fma_f32 v[216:217], v[166:167], v[94:95], v[216:217] op_sel:[0,1,0] op_sel_hi:[1,1,1]
	v_pk_fma_f32 v[216:217], v[168:169], v[96:97], v[216:217] op_sel_hi:[1,0,1]
	v_pk_fma_f32 v[216:217], v[170:171], v[96:97], v[216:217] op_sel:[0,1,0] op_sel_hi:[1,1,1]
	s_waitcnt lgkmcnt(0)
	ds_read_b128 v[78:81], v207 offset:16640
	ds_read_b128 v[82:85], v207 offset:41216
	ds_read_b128 v[86:89], v207 offset:24832
	ds_read_b128 v[90:93], v207 offset:33024
	ds_read_b128 v[94:97], v207 offset:256
	ds_read_b32 v98, v208 offset:8448
	ds_read_b32 v99, v211 offset:8448
	v_pk_mul_f32 v[212:213], v[164:165], v[118:119] op_sel_hi:[1,0]
	v_pk_fma_f32 v[212:213], v[166:167], v[118:119], v[212:213] op_sel:[0,1,0] op_sel_hi:[1,1,1]
	v_add_f32_dpp v224, v217, v216 quad_perm:[1,0,3,2] row_mask:0xf bank_mask:0xf
	v_pk_fma_f32 v[212:213], v[168:169], v[120:121], v[212:213] op_sel_hi:[1,0,1]
	v_pk_fma_f32 v[212:213], v[170:171], v[120:121], v[212:213] op_sel:[0,1,0] op_sel_hi:[1,1,1]
	v_add_f32_dpp v224, v224, v224 quad_perm:[2,3,0,1] row_mask:0xf bank_mask:0xf
	v_pk_mul_f32 v[164:165], v[130:131], v[164:165] op_sel_hi:[0,1]
	v_pk_mul_f32 v[166:167], v[130:131], v[166:167] op_sel:[1,0] op_sel_hi:[1,1]
	v_add_f32_dpp v220, v213, v212 quad_perm:[1,0,3,2] row_mask:0xf bank_mask:0xf
	v_add_f32_dpp v224, v224, v224 row_ror:4 row_mask:0xf bank_mask:0xf
	v_pk_mul_f32 v[168:169], v[132:133], v[168:169] op_sel_hi:[0,1]
	v_add_f32_dpp v220, v220, v220 quad_perm:[2,3,0,1] row_mask:0xf bank_mask:0xf
	v_add_f32_dpp v224, v224, v224 row_ror:8 row_mask:0xf bank_mask:0xf
	v_pk_mul_f32 v[170:171], v[132:133], v[170:171] op_sel:[1,0] op_sel_hi:[1,1]
	v_pk_fma_f32 v[164:165], v[126:127], v[138:139], v[164:165] op_sel_hi:[0,1,1]
	v_add_f32_dpp v220, v220, v220 row_ror:4 row_mask:0xf bank_mask:0xf
	ds_write_b32 v209, v224 offset:49920
	v_pk_fma_f32 v[166:167], v[126:127], v[138:139], v[166:167] op_sel:[1,0,0] op_sel_hi:[1,1,1]
	v_pk_fma_f32 v[168:169], v[128:129], v[138:139], v[168:169] op_sel_hi:[0,1,1]
	v_add_f32_dpp v220, v220, v220 row_ror:8 row_mask:0xf bank_mask:0xf
	v_pk_fma_f32 v[170:171], v[128:129], v[138:139], v[170:171] op_sel:[1,0,0] op_sel_hi:[1,1,1]
	s_nop 0
	v_mov_b32_dpp v221, v220 quad_perm:[1,0,3,2] row_mask:0xf bank_mask:0xf
	v_pk_fma_f32 v[164:165], v[122:123], v[220:221], v[164:165] op_sel_hi:[0,1,1] neg_lo:[0,1,0] neg_hi:[0,1,0]
	v_pk_fma_f32 v[166:167], v[122:123], v[220:221], v[166:167] op_sel:[1,0,0] op_sel_hi:[1,1,1] neg_lo:[0,1,0] neg_hi:[0,1,0]
	v_pk_fma_f32 v[168:169], v[124:125], v[220:221], v[168:169] op_sel_hi:[0,1,1] neg_lo:[0,1,0] neg_hi:[0,1,0]
	v_pk_fma_f32 v[170:171], v[124:125], v[220:221], v[170:171] op_sel:[1,0,0] op_sel_hi:[1,1,1] neg_lo:[0,1,0] neg_hi:[0,1,0]
	v_pk_mul_f32 v[216:217], v[164:165], v[134:135] op_sel_hi:[1,0]
	v_pk_fma_f32 v[216:217], v[166:167], v[134:135], v[216:217] op_sel:[0,1,0] op_sel_hi:[1,1,1]
	v_pk_fma_f32 v[216:217], v[168:169], v[136:137], v[216:217] op_sel_hi:[1,0,1]
	v_pk_fma_f32 v[216:217], v[170:171], v[136:137], v[216:217] op_sel:[0,1,0] op_sel_hi:[1,1,1]
	s_waitcnt lgkmcnt(0)
	ds_read_b128 v[118:121], v207 offset:16384
	ds_read_b128 v[122:125], v207 offset:40960
	ds_read_b128 v[126:129], v207 offset:24576
	ds_read_b128 v[130:133], v207 offset:32768
	ds_read_b128 v[134:137], v207 offset:0
	ds_read_b32 v138, v208 offset:8192
	ds_read_b32 v139, v211 offset:8192
	v_pk_mul_f32 v[212:213], v[164:165], v[78:79] op_sel_hi:[1,0]
	v_pk_fma_f32 v[212:213], v[166:167], v[78:79], v[212:213] op_sel:[0,1,0] op_sel_hi:[1,1,1]
	v_add_f32_dpp v224, v217, v216 quad_perm:[1,0,3,2] row_mask:0xf bank_mask:0xf
	v_pk_fma_f32 v[212:213], v[168:169], v[80:81], v[212:213] op_sel_hi:[1,0,1]
	v_pk_fma_f32 v[212:213], v[170:171], v[80:81], v[212:213] op_sel:[0,1,0] op_sel_hi:[1,1,1]
	v_add_f32_dpp v224, v224, v224 quad_perm:[2,3,0,1] row_mask:0xf bank_mask:0xf
	v_pk_mul_f32 v[164:165], v[90:91], v[164:165] op_sel_hi:[0,1]
	v_pk_mul_f32 v[166:167], v[90:91], v[166:167] op_sel:[1,0] op_sel_hi:[1,1]
	v_add_f32_dpp v220, v213, v212 quad_perm:[1,0,3,2] row_mask:0xf bank_mask:0xf
	v_add_f32_dpp v224, v224, v224 row_ror:4 row_mask:0xf bank_mask:0xf
	v_pk_mul_f32 v[168:169], v[92:93], v[168:169] op_sel_hi:[0,1]
	v_add_f32_dpp v220, v220, v220 quad_perm:[2,3,0,1] row_mask:0xf bank_mask:0xf
	v_add_f32_dpp v224, v224, v224 row_ror:8 row_mask:0xf bank_mask:0xf
	v_pk_mul_f32 v[170:171], v[92:93], v[170:171] op_sel:[1,0] op_sel_hi:[1,1]
	v_pk_fma_f32 v[164:165], v[86:87], v[98:99], v[164:165] op_sel_hi:[0,1,1]
	v_add_f32_dpp v220, v220, v220 row_ror:4 row_mask:0xf bank_mask:0xf
	ds_write_b32 v209, v224 offset:49664
	v_pk_fma_f32 v[166:167], v[86:87], v[98:99], v[166:167] op_sel:[1,0,0] op_sel_hi:[1,1,1]
	v_pk_fma_f32 v[168:169], v[88:89], v[98:99], v[168:169] op_sel_hi:[0,1,1]
	v_add_f32_dpp v220, v220, v220 row_ror:8 row_mask:0xf bank_mask:0xf
	v_pk_fma_f32 v[170:171], v[88:89], v[98:99], v[170:171] op_sel:[1,0,0] op_sel_hi:[1,1,1]
	s_nop 0
	v_mov_b32_dpp v221, v220 quad_perm:[1,0,3,2] row_mask:0xf bank_mask:0xf
	v_pk_fma_f32 v[164:165], v[82:83], v[220:221], v[164:165] op_sel_hi:[0,1,1] neg_lo:[0,1,0] neg_hi:[0,1,0]
	v_pk_fma_f32 v[166:167], v[82:83], v[220:221], v[166:167] op_sel:[1,0,0] op_sel_hi:[1,1,1] neg_lo:[0,1,0] neg_hi:[0,1,0]
	v_pk_fma_f32 v[168:169], v[84:85], v[220:221], v[168:169] op_sel_hi:[0,1,1] neg_lo:[0,1,0] neg_hi:[0,1,0]
	v_pk_fma_f32 v[170:171], v[84:85], v[220:221], v[170:171] op_sel:[1,0,0] op_sel_hi:[1,1,1] neg_lo:[0,1,0] neg_hi:[0,1,0]
	v_pk_mul_f32 v[216:217], v[164:165], v[94:95] op_sel_hi:[1,0]
	v_pk_fma_f32 v[216:217], v[166:167], v[94:95], v[216:217] op_sel:[0,1,0] op_sel_hi:[1,1,1]
	v_pk_fma_f32 v[216:217], v[168:169], v[96:97], v[216:217] op_sel_hi:[1,0,1]
	v_pk_fma_f32 v[216:217], v[170:171], v[96:97], v[216:217] op_sel:[0,1,0] op_sel_hi:[1,1,1]
	s_waitcnt lgkmcnt(0)
	s_cmp_eq_u32 s11, 7
	s_cbranch_scc1 .Lscan_rev_nopf
	v_add_u32_e32 v207, s12, v207
	v_add_u32_e32 v208, s12, v208
	v_add_u32_e32 v211, s12, v211
	ds_read_b128 v[78:81], v207 offset:17152
	ds_read_b128 v[82:85], v207 offset:41728
	ds_read_b128 v[86:89], v207 offset:25344
	ds_read_b128 v[90:93], v207 offset:33536
	ds_read_b128 v[94:97], v207 offset:768
	ds_read_b32 v98, v208 offset:8960
	ds_read_b32 v99, v211 offset:8960
.Lscan_rev_nopf:
	v_pk_mul_f32 v[212:213], v[164:165], v[118:119] op_sel_hi:[1,0]
	v_pk_fma_f32 v[212:213], v[166:167], v[118:119], v[212:213] op_sel:[0,1,0] op_sel_hi:[1,1,1]
	v_add_f32_dpp v224, v217, v216 quad_perm:[1,0,3,2] row_mask:0xf bank_mask:0xf
	v_pk_fma_f32 v[212:213], v[168:169], v[120:121], v[212:213] op_sel_hi:[1,0,1]
	v_pk_fma_f32 v[212:213], v[170:171], v[120:121], v[212:213] op_sel:[0,1,0] op_sel_hi:[1,1,1]
	v_add_f32_dpp v224, v224, v224 quad_perm:[2,3,0,1] row_mask:0xf bank_mask:0xf
	v_pk_mul_f32 v[164:165], v[130:131], v[164:165] op_sel_hi:[0,1]
	v_pk_mul_f32 v[166:167], v[130:131], v[166:167] op_sel:[1,0] op_sel_hi:[1,1]
	v_add_f32_dpp v220, v213, v212 quad_perm:[1,0,3,2] row_mask:0xf bank_mask:0xf
	v_add_f32_dpp v224, v224, v224 row_ror:4 row_mask:0xf bank_mask:0xf
	v_pk_mul_f32 v[168:169], v[132:133], v[168:169] op_sel_hi:[0,1]
	v_add_f32_dpp v220, v220, v220 quad_perm:[2,3,0,1] row_mask:0xf bank_mask:0xf
	v_add_f32_dpp v224, v224, v224 row_ror:8 row_mask:0xf bank_mask:0xf
	v_pk_mul_f32 v[170:171], v[132:133], v[170:171] op_sel:[1,0] op_sel_hi:[1,1]
	v_pk_fma_f32 v[164:165], v[126:127], v[138:139], v[164:165] op_sel_hi:[0,1,1]
	v_add_f32_dpp v220, v220, v220 row_ror:4 row_mask:0xf bank_mask:0xf
	ds_write_b32 v209, v224 offset:49408
	v_pk_fma_f32 v[166:167], v[126:127], v[138:139], v[166:167] op_sel:[1,0,0] op_sel_hi:[1,1,1]
	v_pk_fma_f32 v[168:169], v[128:129], v[138:139], v[168:169] op_sel_hi:[0,1,1]
	v_add_f32_dpp v220, v220, v220 row_ror:8 row_mask:0xf bank_mask:0xf
	v_pk_fma_f32 v[170:171], v[128:129], v[138:139], v[170:171] op_sel:[1,0,0] op_sel_hi:[1,1,1]
	s_nop 0
	v_mov_b32_dpp v221, v220 quad_perm:[1,0,3,2] row_mask:0xf bank_mask:0xf
	v_pk_fma_f32 v[164:165], v[122:123], v[220:221], v[164:165] op_sel_hi:[0,1,1] neg_lo:[0,1,0] neg_hi:[0,1,0]
	v_pk_fma_f32 v[166:167], v[122:123], v[220:221], v[166:167] op_sel:[1,0,0] op_sel_hi:[1,1,1] neg_lo:[0,1,0] neg_hi:[0,1,0]
	v_pk_fma_f32 v[168:169], v[124:125], v[220:221], v[168:169] op_sel_hi:[0,1,1] neg_lo:[0,1,0] neg_hi:[0,1,0]
	v_pk_fma_f32 v[170:171], v[124:125], v[220:221], v[170:171] op_sel:[1,0,0] op_sel_hi:[1,1,1] neg_lo:[0,1,0] neg_hi:[0,1,0]
	v_pk_mul_f32 v[216:217], v[164:165], v[134:135] op_sel_hi:[1,0]
	v_pk_fma_f32 v[216:217], v[166:167], v[134:135], v[216:217] op_sel:[0,1,0] op_sel_hi:[1,1,1]
	v_pk_fma_f32 v[216:217], v[168:169], v[136:137], v[216:217] op_sel_hi:[1,0,1]
	v_pk_fma_f32 v[216:217], v[170:171], v[136:137], v[216:217] op_sel:[0,1,0] op_sel_hi:[1,1,1]
	s_add_i32 s11, s11, 1
	s_cmp_lg_u32 s11, 8
	s_cbranch_scc1 .Lscan_rev_loop
	s_nop 1
	v_add_f32_dpp v224, v217, v216 quad_perm:[1,0,3,2] row_mask:0xf bank_mask:0xf
	s_nop 1
	v_add_f32_dpp v224, v224, v224 quad_perm:[2,3,0,1] row_mask:0xf bank_mask:0xf
	s_nop 1
	v_add_f32_dpp v224, v224, v224 row_ror:4 row_mask:0xf bank_mask:0xf
	s_nop 1
	v_add_f32_dpp v224, v224, v224 row_ror:8 row_mask:0xf bank_mask:0xf
	ds_write_b32 v209, v224 offset:49152
